# v16 + LRU final pass: carry-scan at the item latch issues its 32 LDS reads up front instead of one LDS round trip per step
# speedup vs baseline: 1.0023x; 1.0023x over previous
; __device__ __forceinline__ u32x4 pack8(f32x4 v0, f32x4 v1) { u32x4 w; w.x = cvt_pk_bf16(v0[0], v0[1]); w.y = cvt_pk_bf16(v0[2], v0[3]); w.z = cvt_pk_bf16(v1[0], v1[1]); w.w = cvt_pk_bf16(v1[2], v1[3]); return w; }
; __device__ __forceinline__ void unpack8(u32x4 w, f32x4& v0, f32x4& v1) { v0 = (f32x4){bflo(w.x), bfhi(w.x), bflo(w.y), bfhi(w.y)}; v1 = (f32x4){bflo(w.z), bfhi(w.z), bflo(w.w), bfhi(w.w)}; }
; template <int PASS>
; __device__ void lru_items(const Params& p, unsigned char* shm, int l) {
;     ...
;                 float c = cin;
; #pragma unroll
;                 for (int q = 0; q < 3; ++q) if (q < seg) c = Pq[q * 128 + (tid & 127)] * c + Hq[q * 128 + (tid & 127)];
; #pragma unroll
;                 for (int s = 0; s < 16; ++s) { const int st = seg * 16 + s, t = d ? 63 - st : st; c = As[(d * 64 + t) * 64 + j] * c + Bs[(d * 64 + t) * 64 + j]; Bs[(d * 64 + t) * 64 + j] = c; }
;                 __syncthreads();
;                 const int t = tid >> 3, c8 = tid & 7;
;                 f32x4 g0, g1; unpack8(glv, g0, g1);
;                 const f32x4 f0 = *(const f32x4*)(Bs + t * 64 + c8 * 8), f1 = *(const f32x4*)(Bs + t * 64 + c8 * 8 + 4), r0 = *(const f32x4*)(Bs + (64 + t) * 64 + c8 * 8), r1 = *(const f32x4*)(Bs + (64 + t) * 64 + c8 * 8 + 4);
;                 *(u32x4*)(GL + go) = pack8((f0 + r0) * g0, (f1 + r1) * g1);
.LBB0_199:
	s_or_b64 exec, exec, s[0:1]
	ds_read_b32 v183, v51
	ds_read_b32 v200, v106
	ds_read_b32 v184, v107
	ds_read_b32 v201, v108
	ds_read_b32 v185, v109
	ds_read_b32 v202, v110
	ds_read_b32 v186, v111
	ds_read_b32 v203, v112
	ds_read_b32 v187, v113
	ds_read_b32 v204, v114
	ds_read_b32 v188, v115
	ds_read_b32 v205, v116
	ds_read_b32 v189, v117
	ds_read_b32 v206, v118
	ds_read_b32 v190, v119
	ds_read_b32 v207, v120
	ds_read_b32 v191, v121
	ds_read_b32 v208, v122
	ds_read_b32 v192, v123
	ds_read_b32 v209, v124
	ds_read_b32 v193, v125
	ds_read_b32 v210, v126
	ds_read_b32 v194, v127
	ds_read_b32 v211, v128
	ds_read_b32 v196, v129
	ds_read_b32 v212, v130
	ds_read_b32 v197, v131
	ds_read_b32 v213, v132
	ds_read_b32 v198, v133
	ds_read_b32 v214, v134
	ds_read_b32 v199, v135
	ds_read_b32 v215, v136
	s_waitcnt vmcnt(0)
	v_lshlrev_b32_e32 v172, 16, v10
	v_and_b32_e32 v173, 0xffff0000, v10
	v_lshlrev_b32_e32 v174, 16, v11
	v_and_b32_e32 v175, 0xffff0000, v11
	v_lshlrev_b32_e32 v176, 16, v12
	v_and_b32_e32 v177, 0xffff0000, v12
	v_lshlrev_b32_e32 v178, 16, v13
	v_and_b32_e32 v179, 0xffff0000, v13
	s_waitcnt lgkmcnt(0)
	v_fmac_f32_e32 v200, v34, v183
	ds_write_b32 v106, v200
	v_fmac_f32_e32 v201, v200, v184
	ds_write_b32 v108, v201
	v_fmac_f32_e32 v202, v201, v185
	ds_write_b32 v110, v202
	v_fmac_f32_e32 v203, v202, v186
	ds_write_b32 v112, v203
	v_fmac_f32_e32 v204, v203, v187
	ds_write_b32 v114, v204
	v_fmac_f32_e32 v205, v204, v188
	ds_write_b32 v116, v205
	v_fmac_f32_e32 v206, v205, v189
	ds_write_b32 v118, v206
	v_fmac_f32_e32 v207, v206, v190
	ds_write_b32 v120, v207
	v_fmac_f32_e32 v208, v207, v191
	ds_write_b32 v122, v208
	v_fmac_f32_e32 v209, v208, v192
	ds_write_b32 v124, v209
	v_fmac_f32_e32 v210, v209, v193
	ds_write_b32 v126, v210
	v_fmac_f32_e32 v211, v210, v194
	ds_write_b32 v128, v211
	v_fmac_f32_e32 v212, v211, v196
	ds_write_b32 v130, v212
	v_fmac_f32_e32 v213, v212, v197
	ds_write_b32 v132, v213
	v_fmac_f32_e32 v214, v213, v198
	ds_write_b32 v134, v214
	v_fmac_f32_e32 v215, v214, v199
	ds_write_b32 v136, v215
	v_mov_b64_e32 v[34:35], v[24:25]
	v_mov_b64_e32 v[36:37], v[22:23]
	v_readlane_b32 s0, v253, 61
	s_add_i32 s3, s3, s0
	s_and_b64 vcc, exec, s[46:47]
	s_mov_b32 s5, s4
	v_mov_b32_e32 v159, v151
	v_mov_b32_e32 v160, v154
	v_mov_b32_e32 v161, v153
	v_mov_b32_e32 v162, v152
	v_mov_b32_e32 v163, v150
	v_mov_b32_e32 v164, v157
	v_mov_b32_e32 v165, v158
	v_mov_b32_e32 v166, v40
	v_mov_b32_e32 v167, v41
	v_mov_b32_e32 v168, v155
	v_mov_b32_e32 v169, v156
	v_mov_b32_e32 v170, v38
	v_mov_b32_e32 v171, v39
	s_waitcnt lgkmcnt(0)
	s_barrier
	ds_read_b128 v[10:13], v50 offset:16384
	ds_read_b128 v[14:17], v50
	ds_read_b128 v[18:21], v50 offset:16
	ds_read_b128 v[22:25], v50 offset:16400
	s_waitcnt lgkmcnt(2)
	v_pk_add_f32 v[12:13], v[16:17], v[12:13]
	v_pk_add_f32 v[10:11], v[14:15], v[10:11]
	s_waitcnt lgkmcnt(0)
	v_pk_add_f32 v[14:15], v[20:21], v[24:25]
	v_pk_add_f32 v[16:17], v[18:19], v[22:23]
	v_pk_mul_f32 v[12:13], v[12:13], v[174:175]
	v_pk_mul_f32 v[10:11], v[10:11], v[172:173]
	v_pk_mul_f32 v[14:15], v[14:15], v[178:179]
	v_pk_mul_f32 v[16:17], v[16:17], v[176:177]
	v_cvt_pk_bf16_f32 v10, v10, v11
	v_cvt_pk_bf16_f32 v11, v12, v13
	v_cvt_pk_bf16_f32 v13, v14, v15
	s_nop 0
	v_cvt_pk_bf16_f32 v12, v16, v17
	global_store_dwordx4 v[32:33], v[10:13], off
	s_barrier
	s_cbranch_vccnz .LBB0_220
